# FFN-up epilogue: EDGE row stores issued after the LDS-exchange barrier (and after the conv-weight loads) instead of before it
# speedup vs baseline: 1.0086x; 1.0086x over previous
;     __device__ __forceinline__ void operator()(const f32x4 (&acc)[2][2][4][2], const Unit& u, int wr, int wc, int fr_, int fq_) const {
;     ...
;         if (wr == 0 && fr < 2) {
; #pragma unroll
;             for (int bj = 0; bj < 2; ++bj)
; #pragma unroll
;                 for (int n = 0; n < 2; ++n) *(f32x4*)(EDGE + ((size_t)(u.pm * 4 + fr) * 22 + u.pn) * 256 + 128 * bj + cl + 4 * n) = acc[0][bj][0][n]; }
;         if (wr == 1 && fr >= 14) {
; #pragma unroll
;             for (int bj = 0; bj < 2; ++bj)
; #pragma unroll
;                 for (int n = 0; n < 2; ++n) *(f32x4*)(EDGE + ((size_t)(u.pm * 4 + fr - 12) * 22 + u.pn) * 256 + 128 * bj + cl + 4 * n) = acc[1][bj][3][n]; }
;         asm volatile("s_waitcnt lgkmcnt(0)" ::: "memory"); __builtin_amdgcn_s_barrier(); asm volatile("" ::: "memory");
;         const int chg = u.pn * 128 + cl;
; #pragma unroll
;         for (int n = 0; n < 2; ++n) {
;             f32x4 w0[2], w1[2], w2[2], bv[2];
; #pragma unroll
;             for (int bj = 0; bj < 2; ++bj) { const int wcol = bj * 2816 + chg + 4 * n; w0[bj] = *(const f32x4*)(cw + wcol); w1[bj] = *(const f32x4*)(cw + 5632 + wcol); w2[bj] = *(const f32x4*)(cw + 2 * 5632 + wcol); bv[bj] = *(const f32x4*)(cb + wcol); }
.LBB0_1820:
	v_lshl_add_u32 v178, s14, 7, v160
	v_ashrrev_i32_e32 v179, 31, v178
	v_lshlrev_b64 v[128:129], 2, v[178:179]
	v_lshl_add_u64 v[180:181], s[22:23], 0, v[128:129]
	v_lshl_add_u64 v[130:131], s[28:29], 0, v[128:129]
	v_lshl_add_u64 v[132:133], s[30:31], 0, v[128:129]
	v_lshl_add_u64 v[182:183], s[24:25], 0, v[128:129]
	v_add_u32_e32 v128, 0xb00, v178
	v_ashrrev_i32_e32 v129, 31, v128
	v_lshlrev_b64 v[144:145], 2, v[128:129]
	s_waitcnt lgkmcnt(0)
	s_barrier
	v_lshl_add_u64 v[128:129], s[22:23], 0, v[144:145]
	global_load_dwordx4 v[152:155], v[180:181], off
	global_load_dwordx4 v[148:151], v[130:131], off
	global_load_dwordx4 v[140:143], v[132:133], off
	global_load_dwordx4 v[156:159], v[182:183], off
	v_lshl_add_u64 v[130:131], s[28:29], 0, v[144:145]
	global_load_dwordx4 v[136:139], v[128:129], off
	global_load_dwordx4 v[132:135], v[130:131], off
	v_lshl_add_u64 v[128:129], s[30:31], 0, v[144:145]
	v_lshl_add_u64 v[144:145], s[24:25], 0, v[144:145]
	global_load_dwordx4 v[128:131], v[128:129], off
	v_add_u32_e32 v161, -1, v233
	global_load_dwordx4 v[144:147], v[144:145], off
	v_cmp_gt_i32_e32 vcc, 2, v233
	v_mov_b32_e32 v166, v160
	v_ashrrev_i32_e32 v167, 31, v160
	s_and_b64 s[10:11], s[26:27], vcc
	s_and_saveexec_b64 s[8:9], s[10:11]
	s_cbranch_execz .Ledge_a
	s_ashr_i32 s10, s14, 31
	v_lshl_add_u32 v163, s12, 2, v233
	v_mov_b32_e32 v164, s14
	v_mov_b32_e32 v165, s10
	v_mad_i64_i32 v[164:165], s[10:11], v163, 22, v[164:165]
	v_lshlrev_b64 v[164:165], 10, v[164:165]
	v_lshl_add_u64 v[164:165], s[20:21], 0, v[164:165]
	v_lshl_add_u64 v[164:165], v[166:167], 2, v[164:165]
	global_store_dwordx4 v[164:165], v[124:127], off
	global_store_dwordx4 v[164:165], v[60:63], off offset:16
	global_store_dwordx4 v[164:165], v[116:119], off offset:512
	global_store_dwordx4 v[164:165], v[52:55], off offset:528
.Ledge_a:
	s_or_b64 exec, exec, s[8:9]
	v_cmp_lt_i32_e32 vcc, 13, v233
	s_nop 1
	s_and_b64 s[10:11], s[16:17], vcc
	s_and_saveexec_b64 s[8:9], s[10:11]
	s_cbranch_execz .Ledge_b
	s_lshl_b32 s10, s12, 2
	v_add3_u32 v163, s10, -12, v233
	s_ashr_i32 s10, s14, 31
	v_mov_b32_e32 v164, s14
	v_mov_b32_e32 v165, s10
	v_mad_i64_i32 v[164:165], s[10:11], v163, 22, v[164:165]
	v_lshlrev_b64 v[164:165], 10, v[164:165]
	v_lshl_add_u64 v[164:165], s[20:21], 0, v[164:165]
	v_lshl_add_u64 v[164:165], v[166:167], 2, v[164:165]
	global_store_dwordx4 v[164:165], v[68:71], off
	global_store_dwordx4 v[164:165], v[4:7], off offset:16
	global_store_dwordx4 v[164:165], v[64:67], off offset:512
	global_store_dwordx4 v[164:165], v[0:3], off offset:528
.Ledge_b:
	s_or_b64 exec, exec, s[8:9]
	v_lshl_add_u32 v162, v162, 4, v233
	v_and_b32_e32 v161, 15, v161
	v_add_u32_e32 v163, 1, v233
	v_and_b32_e32 v162, 48, v162
	v_and_b32_e32 v163, 15, v163
	v_or3_b32 v161, v162, v161, v211
	v_lshlrev_b32_e32 v215, 2, v161
	v_or3_b32 v161, v162, v163, v211
	v_cmp_eq_u32_e64 s[10:11], 0, v233
	v_lshlrev_b32_e32 v222, 2, v161
	v_lshl_add_u32 v231, v160, 2, s66
	v_cndmask_b32_e64 v160, v127, v123, s[10:11]
	v_cndmask_b32_e64 v161, v126, v122, s[10:11]
	v_cndmask_b32_e64 v162, v125, v121, s[10:11]
	v_cndmask_b32_e64 v163, v124, v120, s[10:11]
	v_mov_b32_dpp v234, v124 row_ror:1 row_mask:0xf bank_mask:0xf
	s_nop 0
	v_mov_b32_dpp v186, v163 row_ror:15 row_mask:0xf bank_mask:0xf
	v_mov_b32_dpp v236, v125 row_ror:1 row_mask:0xf bank_mask:0xf
	v_mov_b32_dpp v187, v162 row_ror:15 row_mask:0xf bank_mask:0xf
	v_mov_b32_dpp v235, v126 row_ror:1 row_mask:0xf bank_mask:0xf
	v_mov_b32_dpp v192, v161 row_ror:15 row_mask:0xf bank_mask:0xf
	v_mov_b32_dpp v237, v127 row_ror:1 row_mask:0xf bank_mask:0xf
	v_mov_b32_dpp v193, v160 row_ror:15 row_mask:0xf bank_mask:0xf
	v_cndmask_b32_e64 v161, 0, 1, s[16:17]
	v_mov_b32_e32 v160, 0
	v_cmp_ne_u32_e64 s[8:9], 1, v161
	s_andn2_b64 vcc, exec, s[16:17]
	v_mov_b32_e32 v164, 0
	v_mov_b32_e32 v165, 0
	v_mov_b32_e32 v166, 0
	v_mov_b32_e32 v167, 0
	s_cbranch_vccnz .LBB0_1822
	ds_read_b128 v[164:167], v231
